# pre-A w_down weight conversion (layers>0) done only by WGs 128-255, which have one GEMM tile fewer in phase A (load balance, same work)
# speedup vs baseline: 1.0291x; 1.0010x over previous
.LBB0_265:
	s_or_b64 exec, exec, s[4:5]
	v_readlane_b32 s0, v252, 47
	v_readlane_b32 s1, v252, 48
	s_andn2_b64 vcc, exec, s[0:1]
	s_cbranch_vccnz .LBB0_368
	s_cmp_lt_u32 s2, 0x80
	s_cbranch_scc1 .LBB0_368
	s_bfe_i64 s[0:1], s[52:53], 0x200000
	v_readlane_b32 s72, v252, 61
	s_lshl_b64 s[0:1], s[0:1], 13
	v_readlane_b32 s82, v253, 7
	v_readlane_b32 s83, v253, 8
	s_add_u32 s0, s82, s0
	s_addc_u32 s1, s83, s1
	s_mov_b64 s[6:7], s[38:39]
	v_readlane_b32 s36, v254, 50
	s_add_u32 s4, s0, 0xffffe000
	v_readlane_b32 s44, v254, 58
	v_readlane_b32 s80, v253, 5
	s_addc_u32 s5, s1, -1
	s_lshl_b64 s[0:1], s[52:53], 26
	s_lshl_b64 s[12:13], s[52:53], 13
	s_lshl_b64 s[18:19], s[52:53], 24
	s_lshl_b32 s16, s52, 4
	s_lshl_b64 s[20:21], s[52:53], 22
	v_readlane_b32 s38, v254, 52
	v_readlane_b32 s39, v254, 53
	s_lshl_b32 s44, s52, 9
	v_readlane_b32 s81, v253, 6
	s_mov_b64 s[38:39], s[6:7]
	s_add_u32 s6, s80, s0
	v_readlane_b32 s78, v253, 3
	s_addc_u32 s7, s81, s1
	v_readlane_b32 s79, v253, 4
	s_add_u32 s8, s78, s0
	v_readlane_b32 s74, v252, 63
	v_readlane_b32 s40, v254, 54
	s_addc_u32 s9, s79, s1
	v_readlane_b32 s75, v253, 0
	v_readlane_b32 s37, v254, 51
	v_readlane_b32 s41, v254, 55
	s_add_u32 s40, s74, s12
	v_readlane_b32 s42, v254, 56
	s_addc_u32 s41, s75, s13
	s_mov_b32 s1, s37
	v_readlane_b32 s73, v252, 62
	v_readlane_b32 s76, v253, 1
	v_readlane_b32 s77, v253, 2
	v_readlane_b32 s43, v254, 57
	v_readlane_b32 s45, v254, 59
	v_readlane_b32 s46, v254, 60
	v_readlane_b32 s47, v254, 61
	v_readlane_b32 s48, v254, 62
	v_readlane_b32 s49, v254, 63
	s_add_u32 s42, s72, s18
	v_writelane_b32 v254, s0, 50
	s_addc_u32 s43, s73, s19
	v_readlane_b32 s68, v252, 6
	v_writelane_b32 v254, s1, 51
	v_readlane_b32 s84, v253, 9
	v_readlane_b32 s85, v253, 10
	v_readlane_b32 s86, v253, 11
	v_readlane_b32 s87, v253, 12
	v_readlane_b32 s72, v252, 10
	v_readlane_b32 s73, v252, 11
	v_readlane_b32 s74, v252, 12
	v_readlane_b32 s75, v252, 13
	v_readlane_b32 s76, v252, 14
	v_readlane_b32 s77, v252, 15
	v_readlane_b32 s78, v252, 16
	v_readlane_b32 s79, v252, 17
	v_readlane_b32 s80, v252, 18
	v_readlane_b32 s81, v252, 19
	v_readlane_b32 s82, v252, 20
	v_readlane_b32 s83, v252, 21
	v_writelane_b32 v254, s2, 52
	v_writelane_b32 v254, s3, 53
	v_readlane_b32 s72, v252, 22
	v_writelane_b32 v254, s4, 54
	v_readlane_b32 s73, v252, 23
	v_readlane_b32 s74, v252, 24
	v_readlane_b32 s75, v252, 25
	v_readlane_b32 s76, v252, 26
	v_readlane_b32 s77, v252, 27
	v_readlane_b32 s78, v252, 28
	v_readlane_b32 s79, v252, 29
	v_readlane_b32 s80, v252, 30
	v_readlane_b32 s81, v252, 31
	v_readlane_b32 s82, v252, 32
	v_readlane_b32 s83, v252, 33
	v_readlane_b32 s50, v255, 0
	v_readlane_b32 s51, v255, 1
	s_mov_b32 s45, s37
	v_readlane_b32 s69, v252, 7
	s_add_u32 s46, s68, s20
	v_writelane_b32 v254, s5, 55
	v_writelane_b32 v255, s14, 0
	v_readlane_b32 s84, v252, 34
	v_readlane_b32 s85, v252, 35
	v_readlane_b32 s86, v252, 36
	v_readlane_b32 s87, v252, 37
	s_mov_b64 s[72:73], s[76:77]
	s_addc_u32 s47, s69, s21
	v_writelane_b32 v254, s6, 56
	v_writelane_b32 v255, s15, 1
	s_lshl_b64 s[0:1], s[44:45], 2
	s_mov_b64 s[74:75], s[78:79]
	s_mov_b64 s[76:77], s[80:81]
	s_mov_b64 s[78:79], s[82:83]
	s_mov_b64 s[80:81], s[84:85]
	v_writelane_b32 v254, s7, 57
	s_add_u32 s48, s80, s0
	s_mul_i32 s22, s52, 0x300000
	v_writelane_b32 v254, s8, 58
	s_mov_b64 s[82:83], s[86:87]
	s_addc_u32 s49, s81, s1
	s_mul_hi_u32 s17, s52, 0x300000
	v_writelane_b32 v254, s9, 59
	s_add_u32 s50, s82, s22
	v_writelane_b32 v254, s10, 60
	s_addc_u32 s51, s83, s17
	v_writelane_b32 v254, s11, 61
	s_add_u32 s58, s78, s0
	v_readlane_b32 s70, v252, 8
	v_writelane_b32 v254, s12, 62
	s_addc_u32 s59, s79, s1
	s_mul_i32 s1, s52, 0x1880000
	v_readlane_b32 s71, v252, 9
	v_writelane_b32 v254, s13, 63
	s_mul_hi_u32 s0, s52, 0x1880000
	s_add_u32 s70, s76, s1
	s_addc_u32 s71, s77, s0
	s_movk_i32 s17, 0x4000
	s_movk_i32 s18, 0x100
	v_readlane_b32 s19, v254, 38
	v_readlane_b32 s20, v254, 36
	v_readlane_b32 s21, v254, 32
	v_readlane_b32 s22, v252, 46
	s_nop 3
	s_addk_i32 s19, 0xff00
	s_addk_i32 s20, 0xfc00
	s_addk_i32 s21, 0xc000
	s_addk_i32 s22, 0xff80
	s_branch .LBB0_269

.LBB0_268:
	v_readlane_b32 s0, v252, 45
	s_addk_i32 s22, 0x80
	s_add_i32 s21, s21, s17
	s_addk_i32 s20, 0x400
	s_add_i32 s19, s19, s18
	s_cmpk_lt_i32 s22, 0xb30
	s_waitcnt lgkmcnt(0)
	s_cbranch_scc0 .LBB0_367
